# v10: v7 + non-temporal (nt) policy on read-once streams: f32 weight loads in the conversion loops and the layer-0 input-x conversion loads
# speedup vs baseline: 1.0405x; 1.0164x over previous
; __device__ __forceinline__ void tr_item(const float* W, int ldn, int col0, int k0, const float* g, bf16* WT, int ldk, int drow0, LAS float* scr, int lane) {
;     ...
;     for (int i = 0; i < 16; ++i) { const int kk = 4 * i + kr; f32x4 v = *(const f32x4*)(W + (size_t)(k0 + kk) * ldn + col0 + n4); if (g) v = v * g[k0 + kk];
.Ltr_gdone:
	global_load_dwordx4 v[146:149], v232, s[2:3] nt
	v_add_u32_e32 v232, s38, v232
	global_load_dwordx4 v[150:153], v232, s[2:3] nt
	v_add_u32_e32 v232, s38, v232
	global_load_dwordx4 v[154:157], v232, s[2:3] nt
	v_add_u32_e32 v232, s38, v232
	global_load_dwordx4 v[158:161], v232, s[2:3] nt
	v_add_u32_e32 v232, s38, v232
	global_load_dwordx4 v[162:165], v232, s[2:3] nt
	v_add_u32_e32 v232, s38, v232
	global_load_dwordx4 v[166:169], v232, s[2:3] nt
	v_add_u32_e32 v232, s38, v232
	global_load_dwordx4 v[170:173], v232, s[2:3] nt
	v_add_u32_e32 v232, s38, v232
	global_load_dwordx4 v[174:177], v232, s[2:3] nt
	v_add_u32_e32 v232, s38, v232
	global_load_dwordx4 v[178:181], v232, s[2:3] nt
	v_add_u32_e32 v232, s38, v232
	global_load_dwordx4 v[182:185], v232, s[2:3] nt
	v_add_u32_e32 v232, s38, v232
	global_load_dwordx4 v[186:189], v232, s[2:3] nt
	v_add_u32_e32 v232, s38, v232
	global_load_dwordx4 v[190:193], v232, s[2:3] nt
	v_add_u32_e32 v232, s38, v232
	global_load_dwordx4 v[114:117], v232, s[2:3] nt
	v_add_u32_e32 v232, s38, v232
	global_load_dwordx4 v[118:121], v232, s[2:3] nt
	v_add_u32_e32 v232, s38, v232
	global_load_dwordx4 v[122:125], v232, s[2:3] nt
	v_add_u32_e32 v232, s38, v232
	global_load_dwordx4 v[126:129], v232, s[2:3] nt
	s_waitcnt vmcnt(15)
	v_mul_f32_e32 v146, v210, v146
	v_mul_f32_e32 v147, v210, v147
	v_mul_f32_e32 v148, v210, v148
	v_mul_f32_e32 v149, v210, v149
	ds_write2_b32 v242, v146, v147 offset1:1
	ds_write2_b32 v242, v148, v149 offset0:2 offset1:3
	v_add_u32_e32 v242, 0x410, v242
	s_waitcnt vmcnt(14)
	v_mul_f32_e32 v150, v211, v150
	v_mul_f32_e32 v151, v211, v151
	v_mul_f32_e32 v152, v211, v152
	v_mul_f32_e32 v153, v211, v153
	ds_write2_b32 v242, v150, v151 offset1:1
	ds_write2_b32 v242, v152, v153 offset0:2 offset1:3
	v_add_u32_e32 v242, 0x410, v242
	s_waitcnt vmcnt(13)
	v_mul_f32_e32 v154, v212, v154
	v_mul_f32_e32 v155, v212, v155
	v_mul_f32_e32 v156, v212, v156
	v_mul_f32_e32 v157, v212, v157
	ds_write2_b32 v242, v154, v155 offset1:1
	ds_write2_b32 v242, v156, v157 offset0:2 offset1:3
	v_add_u32_e32 v242, 0x410, v242
	s_waitcnt vmcnt(12)
	v_mul_f32_e32 v158, v213, v158
	v_mul_f32_e32 v159, v213, v159
	v_mul_f32_e32 v160, v213, v160
	v_mul_f32_e32 v161, v213, v161
	ds_write2_b32 v242, v158, v159 offset1:1
	ds_write2_b32 v242, v160, v161 offset0:2 offset1:3
	v_add_u32_e32 v242, 0x410, v242
	s_waitcnt vmcnt(11)
	v_mul_f32_e32 v162, v214, v162
	v_mul_f32_e32 v163, v214, v163
	v_mul_f32_e32 v164, v214, v164
	v_mul_f32_e32 v165, v214, v165
	ds_write2_b32 v242, v162, v163 offset1:1
	ds_write2_b32 v242, v164, v165 offset0:2 offset1:3
	v_add_u32_e32 v242, 0x410, v242
	s_waitcnt vmcnt(10)
	v_mul_f32_e32 v166, v215, v166
	v_mul_f32_e32 v167, v215, v167
	v_mul_f32_e32 v168, v215, v168
	v_mul_f32_e32 v169, v215, v169
	ds_write2_b32 v242, v166, v167 offset1:1
	ds_write2_b32 v242, v168, v169 offset0:2 offset1:3
	v_add_u32_e32 v242, 0x410, v242
	s_waitcnt vmcnt(9)
	v_mul_f32_e32 v170, v216, v170
	v_mul_f32_e32 v171, v216, v171
	v_mul_f32_e32 v172, v216, v172
	v_mul_f32_e32 v173, v216, v173
	ds_write2_b32 v242, v170, v171 offset1:1
	ds_write2_b32 v242, v172, v173 offset0:2 offset1:3
	v_add_u32_e32 v242, 0x410, v242
	s_waitcnt vmcnt(8)
	v_mul_f32_e32 v174, v217, v174
	v_mul_f32_e32 v175, v217, v175
	v_mul_f32_e32 v176, v217, v176
	v_mul_f32_e32 v177, v217, v177
	ds_write2_b32 v242, v174, v175 offset1:1
	ds_write2_b32 v242, v176, v177 offset0:2 offset1:3
	v_add_u32_e32 v242, 0x410, v242
	s_waitcnt vmcnt(7)
	v_mul_f32_e32 v178, v218, v178
	v_mul_f32_e32 v179, v218, v179
	v_mul_f32_e32 v180, v218, v180
	v_mul_f32_e32 v181, v218, v181
	ds_write2_b32 v242, v178, v179 offset1:1
	ds_write2_b32 v242, v180, v181 offset0:2 offset1:3
	v_add_u32_e32 v242, 0x410, v242
	s_waitcnt vmcnt(6)
	v_mul_f32_e32 v182, v219, v182
	v_mul_f32_e32 v183, v219, v183
	v_mul_f32_e32 v184, v219, v184
	v_mul_f32_e32 v185, v219, v185
	ds_write2_b32 v242, v182, v183 offset1:1
	ds_write2_b32 v242, v184, v185 offset0:2 offset1:3
	v_add_u32_e32 v242, 0x410, v242
	s_waitcnt vmcnt(5)
	v_mul_f32_e32 v186, v220, v186
	v_mul_f32_e32 v187, v220, v187
	v_mul_f32_e32 v188, v220, v188
	v_mul_f32_e32 v189, v220, v189
	ds_write2_b32 v242, v186, v187 offset1:1
	ds_write2_b32 v242, v188, v189 offset0:2 offset1:3
	v_add_u32_e32 v242, 0x410, v242
	s_waitcnt vmcnt(4)
	v_mul_f32_e32 v190, v221, v190
	v_mul_f32_e32 v191, v221, v191
	v_mul_f32_e32 v192, v221, v192
	v_mul_f32_e32 v193, v221, v193
	ds_write2_b32 v242, v190, v191 offset1:1
	ds_write2_b32 v242, v192, v193 offset0:2 offset1:3
	v_add_u32_e32 v242, 0x410, v242
	s_waitcnt vmcnt(3)
; #define LAS __attribute__((address_space(3)))
; __device__ __forceinline__ unsigned pk2(float lo, float hi) { return f2bf(lo) | (f2bf(hi) << 16); }
; #define LDS_WAIT() asm volatile("s_waitcnt lgkmcnt(0)" ::: "memory")
; __device__ __forceinline__ void tr_item(const float* W, int ldn, int col0, int k0, const float* g, bf16* WT, int ldk, int drow0, LAS float* scr, int lane) {
;     ...
;     LDS_WAIT(); asm volatile("" ::: "memory");
;     const int c = lane & 7;
; #pragma unroll
;     for (int j = 0; j < 8; ++j) { const int n = (lane >> 3) + 8 * j; const LAS float* s = scr + (8 * c) * 65 + n;
;         v4u o; o.x = pk2(s[0 * 65], s[1 * 65]); o.y = pk2(s[2 * 65], s[3 * 65]); o.z = pk2(s[4 * 65], s[5 * 65]); o.w = pk2(s[6 * 65], s[7 * 65]);
;         *(v4u*)(WT + (size_t)(drow0 + n) * ldk + k0 + 8 * c) = o; }
; __device__ __forceinline__ void phase_prologue(PtrTab TB, unsigned char* ws, float* xout, int l, LAS unsigned char* lds, int gw, int NGW, int lane, int wave) {
;     ...
;     for (int it = gw; it < S14; it += NGW) {
	v_mul_f32_e32 v114, v222, v114
	v_mul_f32_e32 v115, v222, v115
	v_mul_f32_e32 v116, v222, v116
	v_mul_f32_e32 v117, v222, v117
	ds_write2_b32 v242, v114, v115 offset1:1
	ds_write2_b32 v242, v116, v117 offset0:2 offset1:3
	v_add_u32_e32 v242, 0x410, v242
	s_waitcnt vmcnt(2)
	v_mul_f32_e32 v118, v223, v118
	v_mul_f32_e32 v119, v223, v119
	v_mul_f32_e32 v120, v223, v120
	v_mul_f32_e32 v121, v223, v121
	ds_write2_b32 v242, v118, v119 offset1:1
	ds_write2_b32 v242, v120, v121 offset0:2 offset1:3
	v_add_u32_e32 v242, 0x410, v242
	s_waitcnt vmcnt(1)
	v_mul_f32_e32 v122, v230, v122
	v_mul_f32_e32 v123, v230, v123
	v_mul_f32_e32 v124, v230, v124
	v_mul_f32_e32 v125, v230, v125
	ds_write2_b32 v242, v122, v123 offset1:1
	ds_write2_b32 v242, v124, v125 offset0:2 offset1:3
	v_add_u32_e32 v242, 0x410, v242
	s_waitcnt vmcnt(0)
	v_mul_f32_e32 v126, v231, v126
	v_mul_f32_e32 v127, v231, v127
	v_mul_f32_e32 v128, v231, v128
	v_mul_f32_e32 v129, v231, v129
	ds_write2_b32 v242, v126, v127 offset1:1
	ds_write2_b32 v242, v128, v129 offset0:2 offset1:3
	s_waitcnt lgkmcnt(0)
	ds_read2_b32 v[146:147], v62 offset0:0 offset1:65
	ds_read2_b32 v[148:149], v62 offset0:130 offset1:195
	ds_read2_b32 v[150:151], v243 offset0:4 offset1:69
	ds_read2_b32 v[152:153], v243 offset0:134 offset1:199
	ds_read2_b32 v[154:155], v62 offset0:8 offset1:73
	ds_read2_b32 v[156:157], v62 offset0:138 offset1:203
	ds_read2_b32 v[158:159], v243 offset0:12 offset1:77
	ds_read2_b32 v[160:161], v243 offset0:142 offset1:207
	ds_read2_b32 v[162:163], v62 offset0:16 offset1:81
	ds_read2_b32 v[164:165], v62 offset0:146 offset1:211
	ds_read2_b32 v[166:167], v243 offset0:20 offset1:85
	ds_read2_b32 v[168:169], v243 offset0:150 offset1:215
	s_waitcnt lgkmcnt(8)
	v_cvt_pk_bf16_f32 v146, v146, v147
	v_cvt_pk_bf16_f32 v147, v148, v149
	v_cvt_pk_bf16_f32 v148, v150, v151
	v_cvt_pk_bf16_f32 v149, v152, v153
	global_store_dwordx4 v244, v[146:149], s[24:25]
	ds_read2_b32 v[170:171], v62 offset0:24 offset1:89
	ds_read2_b32 v[172:173], v62 offset0:154 offset1:219
	ds_read2_b32 v[174:175], v243 offset0:28 offset1:93
	ds_read2_b32 v[176:177], v243 offset0:158 offset1:223
	s_waitcnt lgkmcnt(8)
	v_cvt_pk_bf16_f32 v154, v154, v155
	v_cvt_pk_bf16_f32 v155, v156, v157
	v_cvt_pk_bf16_f32 v156, v158, v159
	v_cvt_pk_bf16_f32 v157, v160, v161
	global_store_dwordx4 v245, v[154:157], s[24:25]
	ds_read2_b32 v[178:179], v62 offset0:32 offset1:97
	ds_read2_b32 v[180:181], v62 offset0:162 offset1:227
	ds_read2_b32 v[182:183], v243 offset0:36 offset1:101
	ds_read2_b32 v[184:185], v243 offset0:166 offset1:231
	s_waitcnt lgkmcnt(8)
	v_cvt_pk_bf16_f32 v162, v162, v163
	v_cvt_pk_bf16_f32 v163, v164, v165
	v_cvt_pk_bf16_f32 v164, v166, v167
	v_cvt_pk_bf16_f32 v165, v168, v169
	global_store_dwordx4 v246, v[162:165], s[24:25]
	ds_read2_b32 v[186:187], v62 offset0:40 offset1:105
	ds_read2_b32 v[188:189], v62 offset0:170 offset1:235
	ds_read2_b32 v[190:191], v243 offset0:44 offset1:109
	ds_read2_b32 v[192:193], v243 offset0:174 offset1:239
	s_waitcnt lgkmcnt(8)
	v_cvt_pk_bf16_f32 v170, v170, v171
	v_cvt_pk_bf16_f32 v171, v172, v173
	v_cvt_pk_bf16_f32 v172, v174, v175
	v_cvt_pk_bf16_f32 v173, v176, v177
	global_store_dwordx4 v247, v[170:173], s[24:25]
	ds_read2_b32 v[114:115], v62 offset0:48 offset1:113
	ds_read2_b32 v[116:117], v62 offset0:178 offset1:243
	ds_read2_b32 v[118:119], v243 offset0:52 offset1:117
	ds_read2_b32 v[120:121], v243 offset0:182 offset1:247
	s_waitcnt lgkmcnt(8)
	v_cvt_pk_bf16_f32 v178, v178, v179
	v_cvt_pk_bf16_f32 v179, v180, v181
	v_cvt_pk_bf16_f32 v180, v182, v183
	v_cvt_pk_bf16_f32 v181, v184, v185
	global_store_dwordx4 v248, v[178:181], s[24:25]
	ds_read2_b32 v[122:123], v62 offset0:56 offset1:121
	ds_read2_b32 v[124:125], v62 offset0:186 offset1:251
	ds_read2_b32 v[126:127], v243 offset0:60 offset1:125
	ds_read2_b32 v[128:129], v243 offset0:190 offset1:255
	s_waitcnt lgkmcnt(8)
	v_cvt_pk_bf16_f32 v186, v186, v187
	v_cvt_pk_bf16_f32 v187, v188, v189
	v_cvt_pk_bf16_f32 v188, v190, v191
	v_cvt_pk_bf16_f32 v189, v192, v193
	global_store_dwordx4 v249, v[186:189], s[24:25]
	s_waitcnt lgkmcnt(4)
	v_cvt_pk_bf16_f32 v114, v114, v115
	v_cvt_pk_bf16_f32 v115, v116, v117
	v_cvt_pk_bf16_f32 v116, v118, v119
	v_cvt_pk_bf16_f32 v117, v120, v121
	global_store_dwordx4 v250, v[114:117], s[24:25]
	s_waitcnt lgkmcnt(0)
	v_cvt_pk_bf16_f32 v122, v122, v123
	v_cvt_pk_bf16_f32 v123, v124, v125
	v_cvt_pk_bf16_f32 v124, v126, v127
	v_cvt_pk_bf16_f32 v125, v128, v129
	global_store_dwordx4 v251, v[122:125], s[24:25]
	s_cmpk_eq_u32 s8, 0x800
	s_cbranch_scc0 .LBB0_22
	s_cmpk_lg_u32 s94, 0
	s_cbranch_scc1 .Ltr_l1
	s_cmpk_ge_u32 s71, 0x1800
	s_cbranch_scc1 .Ltr_hi
	s_addk_i32 s71, 0x800
	s_cmpk_lt_u32 s71, 0x1800
	s_cbranch_scc1 .LBB0_23
	s_cmpk_lt_u32 s10, 0x400
	s_cbranch_scc1 .LBB0_214
	s_sub_u32 s71, s71, 0x400
	s_branch .LBB0_23

; __device__ __forceinline__ float bperm(float v, int srclane) { return __int_as_float(__builtin_amdgcn_ds_bpermute(srclane << 2, __float_as_int(v))); }
; __device__ __forceinline__ unsigned pk2(float lo, float hi) { return f2bf(lo) | (f2bf(hi) << 16); }
; __device__ __forceinline__ float bperm(float v, int srclane) { return __int_as_float(__builtin_amdgcn_ds_bpermute(srclane << 2, __float_as_int(v))); }
; __device__ __forceinline__ void phase_prologue(PtrTab TB, unsigned char* ws, float* xout, int l, LAS unsigned char* lds, int gw, int NGW, int lane, int wave) {
;     ...
;         for (int r0 = gw; r0 < M; r0 += 4 * NGW) { f32x4 v[4][4]; float s[4];
; #pragma unroll
;             for (int q = 0; q < 4; ++q) { const int r = (r0 + q * NGW < M) ? r0 + q * NGW : r0; const f32x4* xr = (const f32x4*)(x + (size_t)r * D) + lane; s[q] = 0.f;
; #pragma unroll
;                 for (int j = 0; j < 4; ++j) { v[q][j] = xr[64 * j]; s[q] += (v[q][j].x * v[q][j].x + v[q][j].y * v[q][j].y) + (v[q][j].z * v[q][j].z + v[q][j].w * v[q][j].w); } }
; #pragma unroll
;             for (int o = 1; o < 64; o <<= 1) {
; #pragma unroll
;                 for (int q = 0; q < 4; ++q) s[q] += bperm(s[q], lane ^ o); }
; #pragma unroll
;             for (int q = 0; q < 4; ++q) { const int r = r0 + q * NGW; if (r < M) { unsigned long long* o8 = (unsigned long long*)(xb + (size_t)r * D) + lane;
;                     if (lane < 4) ss[(size_t)r * 4 + lane] = lane == 0 ? s[q] : 0.f;
; #pragma unroll
;                     for (int j = 0; j < 4; ++j) { o8[64 * j] = (unsigned long long)pk2(v[q][j].x, v[q][j].y) | ((unsigned long long)pk2(v[q][j].z, v[q][j].w) << 32); } } }
.LBB0_230:
	s_add_i32 s44, s8, s10
	s_cmpk_lt_i32 s44, 0x4000
	s_cselect_b64 s[60:61], -1, 0
	s_and_b64 s[6:7], s[60:61], exec
	s_cselect_b32 s6, s44, s10
	global_load_dwordx4 v[60:63], v[76:77], off offset:-2048 nt
	global_load_dwordx4 v[56:59], v[76:77], off offset:-1024 nt
	global_load_dwordx4 v[52:55], v[76:77], off nt
	global_load_dwordx4 v[48:51], v[76:77], off offset:1024 nt
	s_ashr_i32 s7, s6, 31
	s_lshl_b64 s[6:7], s[6:7], 12
	s_add_i32 s30, s9, s10
	s_cmpk_lt_i32 s30, 0x4000
	s_cselect_b64 s[38:39], -1, 0
	v_lshl_add_u64 v[0:1], v[66:67], 0, s[6:7]
	s_and_b64 s[6:7], s[38:39], exec
	global_load_dwordx4 v[44:47], v[0:1], off nt
	global_load_dwordx4 v[40:43], v[0:1], off offset:1024 nt
	global_load_dwordx4 v[36:39], v[0:1], off offset:2048 nt
	global_load_dwordx4 v[32:35], v[0:1], off offset:3072 nt
	s_cselect_b32 s6, s30, s10
	s_ashr_i32 s7, s6, 31
	s_lshl_b64 s[6:7], s[6:7], 12
	v_lshl_add_u64 v[0:1], v[66:67], 0, s[6:7]
	global_load_dwordx4 v[28:31], v[0:1], off nt
	global_load_dwordx4 v[24:27], v[0:1], off offset:1024 nt
	global_load_dwordx4 v[16:19], v[0:1], off offset:2048 nt
	s_add_i32 s18, s22, s10
	s_cmpk_lt_i32 s18, 0x4000
	global_load_dwordx4 v[20:23], v[0:1], off offset:3072 nt
	s_cselect_b64 s[20:21], -1, 0
	s_and_b64 s[6:7], s[20:21], exec
	s_cselect_b32 s6, s18, s10
	s_ashr_i32 s7, s6, 31
	s_lshl_b64 s[6:7], s[6:7], 12
	v_lshl_add_u64 v[0:1], v[66:67], 0, s[6:7]
	global_load_dwordx4 v[12:15], v[0:1], off nt
	global_load_dwordx4 v[8:11], v[0:1], off offset:1024 nt
	global_load_dwordx4 v[4:7], v[0:1], off offset:2048 nt
	s_nop 0
	global_load_dwordx4 v[0:3], v[0:1], off offset:3072 nt
	s_waitcnt vmcnt(15)
	v_mul_f32_e32 v83, v61, v61
	s_waitcnt lgkmcnt(0)
	v_mul_f32_e32 v84, v63, v63
	s_waitcnt vmcnt(14)
	v_mul_f32_e32 v85, v57, v57
	v_mul_f32_e32 v86, v59, v59
	s_waitcnt vmcnt(13)
	v_mul_f32_e32 v87, v53, v53
	v_mul_f32_e32 v88, v55, v55
	v_fmac_f32_e32 v83, v60, v60
	v_fmac_f32_e32 v84, v62, v62
	v_fmac_f32_e32 v85, v56, v56
	v_fmac_f32_e32 v86, v58, v58
	s_waitcnt vmcnt(12)
	v_mul_f32_e32 v89, v49, v49
	v_mul_f32_e32 v90, v51, v51
	v_fmac_f32_e32 v87, v52, v52
	v_fmac_f32_e32 v88, v54, v54
	v_add_f32_e32 v83, v83, v84
	v_add_f32_e32 v84, v85, v86
	v_fmac_f32_e32 v89, v48, v48
	v_fmac_f32_e32 v90, v50, v50
	v_add_f32_e32 v85, v87, v88
	v_add_f32_e32 v83, v83, v84
	v_add_f32_e32 v86, v89, v90
	v_add_f32_e32 v83, v83, v85
	v_add_f32_e32 v83, v83, v86
	s_waitcnt vmcnt(11)
	v_mul_f32_e32 v84, v45, v45
	v_mul_f32_e32 v85, v47, v47
	s_waitcnt vmcnt(10)
	v_mul_f32_e32 v86, v41, v41
	v_mul_f32_e32 v87, v43, v43
	s_waitcnt vmcnt(9)
	v_mul_f32_e32 v88, v37, v37
	v_mul_f32_e32 v89, v39, v39
	v_fmac_f32_e32 v84, v44, v44
	v_fmac_f32_e32 v85, v46, v46
	v_fmac_f32_e32 v86, v40, v40
	v_fmac_f32_e32 v87, v42, v42
	s_waitcnt vmcnt(8)
	v_mul_f32_e32 v90, v33, v33
	v_mul_f32_e32 v91, v35, v35
	v_fmac_f32_e32 v88, v36, v36
	v_fmac_f32_e32 v89, v38, v38
	v_add_f32_e32 v84, v84, v85
	v_add_f32_e32 v85, v86, v87
	v_fmac_f32_e32 v90, v32, v32
	v_fmac_f32_e32 v91, v34, v34
	v_add_f32_e32 v86, v88, v89
	v_add_f32_e32 v84, v84, v85
	v_add_f32_e32 v87, v90, v91
	v_add_f32_e32 v84, v84, v86
	v_add_f32_e32 v84, v84, v87
	s_waitcnt vmcnt(7)
	v_mul_f32_e32 v85, v29, v29
	v_mul_f32_e32 v86, v31, v31
	s_waitcnt vmcnt(6)
	v_mul_f32_e32 v87, v25, v25
	v_mul_f32_e32 v88, v27, v27
	v_fmac_f32_e32 v85, v28, v28
	v_fmac_f32_e32 v86, v30, v30
	v_fmac_f32_e32 v87, v24, v24
	v_fmac_f32_e32 v88, v26, v26
	v_add_f32_e32 v85, v85, v86
	v_add_f32_e32 v86, v87, v88
	s_waitcnt vmcnt(5)
	v_mul_f32_e32 v89, v17, v17
	v_add_f32_e32 v85, v85, v86
	v_mul_f32_e32 v86, v19, v19
	v_fmac_f32_e32 v89, v16, v16
	v_fmac_f32_e32 v86, v18, v18
	v_add_f32_e32 v86, v89, v86
	v_add_f32_e32 v85, v85, v86
	s_waitcnt vmcnt(4)
	v_mul_f32_e32 v86, v21, v21
	v_mul_f32_e32 v87, v23, v23
	v_fmac_f32_e32 v86, v20, v20
	v_fmac_f32_e32 v87, v22, v22
	v_add_f32_e32 v86, v86, v87
	v_add_f32_e32 v85, v85, v86
	s_waitcnt vmcnt(3)
	v_mul_f32_e32 v86, v13, v13
	v_mul_f32_e32 v87, v15, v15
	v_fmac_f32_e32 v86, v12, v12
	v_fmac_f32_e32 v87, v14, v14
	v_add_f32_e32 v86, v86, v87
	s_waitcnt vmcnt(2)
	v_mul_f32_e32 v87, v9, v9
	v_mul_f32_e32 v88, v11, v11
	v_fmac_f32_e32 v87, v8, v8
	v_fmac_f32_e32 v88, v10, v10
	v_add_f32_e32 v87, v87, v88
	v_add_f32_e32 v86, v86, v87
	s_waitcnt vmcnt(1)
	v_mul_f32_e32 v87, v5, v5
	v_mul_f32_e32 v88, v7, v7
	v_fmac_f32_e32 v87, v4, v4
	v_fmac_f32_e32 v88, v6, v6
	v_add_f32_e32 v87, v87, v88
	v_add_f32_e32 v86, v86, v87
	s_waitcnt vmcnt(0)
	v_mul_f32_e32 v87, v1, v1
	v_mul_f32_e32 v88, v3, v3
	v_fmac_f32_e32 v87, v0, v0
	v_fmac_f32_e32 v88, v2, v2
	v_add_f32_e32 v87, v87, v88
	v_add_f32_e32 v86, v86, v87
	ds_bpermute_b32 v87, v64, v83
	ds_bpermute_b32 v88, v64, v84
	ds_bpermute_b32 v89, v64, v85
	ds_bpermute_b32 v90, v64, v86
	s_waitcnt lgkmcnt(3)
	v_add_f32_e32 v83, v83, v87
	s_waitcnt lgkmcnt(2)
	v_add_f32_e32 v84, v84, v88
	s_waitcnt lgkmcnt(1)
	v_add_f32_e32 v85, v85, v89
	s_waitcnt lgkmcnt(0)
	v_add_f32_e32 v86, v86, v90
	ds_bpermute_b32 v87, v78, v83
	ds_bpermute_b32 v88, v78, v84
	ds_bpermute_b32 v89, v78, v85
	ds_bpermute_b32 v90, v78, v86
	s_waitcnt lgkmcnt(3)
	v_add_f32_e32 v83, v83, v87
	s_waitcnt lgkmcnt(2)
	v_add_f32_e32 v84, v84, v88
	s_waitcnt lgkmcnt(1)
	v_add_f32_e32 v85, v85, v89
	s_waitcnt lgkmcnt(0)
	v_add_f32_e32 v86, v86, v90
	ds_bpermute_b32 v87, v79, v83
	ds_bpermute_b32 v88, v79, v84
	ds_bpermute_b32 v89, v79, v85
	ds_bpermute_b32 v90, v79, v86
	s_waitcnt lgkmcnt(3)
	v_add_f32_e32 v83, v83, v87
	s_waitcnt lgkmcnt(2)
	v_add_f32_e32 v84, v84, v88
	s_waitcnt lgkmcnt(1)
	v_add_f32_e32 v85, v85, v89
	s_waitcnt lgkmcnt(0)
	v_add_f32_e32 v86, v86, v90
	ds_bpermute_b32 v87, v80, v83
	ds_bpermute_b32 v88, v80, v84
	ds_bpermute_b32 v89, v80, v85
	ds_bpermute_b32 v90, v80, v86
	s_waitcnt lgkmcnt(3)
	v_add_f32_e32 v83, v83, v87
	s_waitcnt lgkmcnt(2)
	v_add_f32_e32 v84, v84, v88
	s_waitcnt lgkmcnt(1)
	v_add_f32_e32 v85, v85, v89
	s_waitcnt lgkmcnt(0)
	v_add_f32_e32 v86, v86, v90
	ds_bpermute_b32 v87, v81, v83
	ds_bpermute_b32 v88, v81, v84
	ds_bpermute_b32 v90, v81, v85
	ds_bpermute_b32 v91, v81, v86
	s_waitcnt lgkmcnt(3)
	v_add_f32_e32 v89, v83, v87
	s_waitcnt lgkmcnt(2)
	v_add_f32_e32 v87, v84, v88
	s_waitcnt lgkmcnt(1)
	v_add_f32_e32 v85, v85, v90
	s_waitcnt lgkmcnt(0)
	v_add_f32_e32 v83, v86, v91
	ds_bpermute_b32 v90, v82, v89
	ds_bpermute_b32 v88, v82, v87
	ds_bpermute_b32 v86, v82, v85
	ds_bpermute_b32 v84, v82, v83
	s_and_saveexec_b64 s[6:7], s[2:3]
	s_cbranch_execz .LBB0_232
	s_waitcnt lgkmcnt(3)
	v_add_f32_e32 v89, v89, v90
	v_lshl_add_u64 v[92:93], s[82:83], 0, v[72:73]
	v_cndmask_b32_e64 v89, 0, v89, s[4:5]
	global_store_dword v[92:93], v89, off

; #define LAS __attribute__((address_space(3)))
; __device__ __forceinline__ void tr_item(const float* W, int ldn, int col0, int k0, const float* g, bf16* WT, int ldk, int drow0, LAS float* scr, int lane) {
;     ...
;     for (int i = 0; i < 16; ++i) { const int kk = 4 * i + kr; f32x4 v = *(const f32x4*)(W + (size_t)(k0 + kk) * ldn + col0 + n4); if (g) v = v * g[k0 + kk];
;         LAS float* d = scr + kk * 65 + n4; d[0] = v.x; d[1] = v.y; d[2] = v.z; d[3] = v.w; }
.Lofl_gdone:
	global_load_dwordx4 v[146:149], v232, s[2:3] nt
	v_add_u32_e32 v232, s38, v232
	global_load_dwordx4 v[150:153], v232, s[2:3] nt
	v_add_u32_e32 v232, s38, v232
	global_load_dwordx4 v[154:157], v232, s[2:3] nt
	v_add_u32_e32 v232, s38, v232
	global_load_dwordx4 v[158:161], v232, s[2:3] nt
	v_add_u32_e32 v232, s38, v232
	global_load_dwordx4 v[166:169], v232, s[2:3] nt
	v_add_u32_e32 v232, s38, v232
	global_load_dwordx4 v[170:173], v232, s[2:3] nt
	v_add_u32_e32 v232, s38, v232
	global_load_dwordx4 v[174:177], v232, s[2:3] nt
	v_add_u32_e32 v232, s38, v232
	global_load_dwordx4 v[178:181], v232, s[2:3] nt
	v_add_u32_e32 v232, s38, v232
	global_load_dwordx4 v[182:185], v232, s[2:3] nt
	v_add_u32_e32 v232, s38, v232
	global_load_dwordx4 v[186:189], v232, s[2:3] nt
	v_add_u32_e32 v232, s38, v232
	global_load_dwordx4 v[190:193], v232, s[2:3] nt
	v_add_u32_e32 v232, s38, v232
	global_load_dwordx4 v[108:111], v232, s[2:3] nt
	v_add_u32_e32 v232, s38, v232
	global_load_dwordx4 v[112:115], v232, s[2:3] nt
	v_add_u32_e32 v232, s38, v232
	global_load_dwordx4 v[116:119], v232, s[2:3] nt
	v_add_u32_e32 v232, s38, v232
	global_load_dwordx4 v[120:123], v232, s[2:3] nt
	v_add_u32_e32 v232, s38, v232
	global_load_dwordx4 v[124:127], v232, s[2:3] nt
	s_waitcnt vmcnt(15)
	v_mul_f32_e32 v146, v210, v146
	v_mul_f32_e32 v147, v210, v147
	v_mul_f32_e32 v148, v210, v148
	v_mul_f32_e32 v149, v210, v149
	ds_write2_b32 v242, v146, v147 offset1:1
	ds_write2_b32 v242, v148, v149 offset0:2 offset1:3
	v_add_u32_e32 v242, 0x410, v242
	s_waitcnt vmcnt(14)
	v_mul_f32_e32 v150, v211, v150
	v_mul_f32_e32 v151, v211, v151
	v_mul_f32_e32 v152, v211, v152
	v_mul_f32_e32 v153, v211, v153
	ds_write2_b32 v242, v150, v151 offset1:1
	ds_write2_b32 v242, v152, v153 offset0:2 offset1:3
	v_add_u32_e32 v242, 0x410, v242
	s_waitcnt vmcnt(13)
	v_mul_f32_e32 v154, v212, v154
	v_mul_f32_e32 v155, v212, v155
	v_mul_f32_e32 v156, v212, v156
	v_mul_f32_e32 v157, v212, v157
	ds_write2_b32 v242, v154, v155 offset1:1
	ds_write2_b32 v242, v156, v157 offset0:2 offset1:3
	v_add_u32_e32 v242, 0x410, v242
	s_waitcnt vmcnt(12)
	v_mul_f32_e32 v158, v213, v158
	v_mul_f32_e32 v159, v213, v159
	v_mul_f32_e32 v160, v213, v160
	v_mul_f32_e32 v161, v213, v161
	ds_write2_b32 v242, v158, v159 offset1:1
	ds_write2_b32 v242, v160, v161 offset0:2 offset1:3
	v_add_u32_e32 v242, 0x410, v242
	s_waitcnt vmcnt(11)
	v_mul_f32_e32 v166, v214, v166
	v_mul_f32_e32 v167, v214, v167
	v_mul_f32_e32 v168, v214, v168
	v_mul_f32_e32 v169, v214, v169
	ds_write2_b32 v242, v166, v167 offset1:1
	ds_write2_b32 v242, v168, v169 offset0:2 offset1:3
	v_add_u32_e32 v242, 0x410, v242
	s_waitcnt vmcnt(10)
	v_mul_f32_e32 v170, v215, v170
	v_mul_f32_e32 v171, v215, v171
	v_mul_f32_e32 v172, v215, v172
	v_mul_f32_e32 v173, v215, v173
	ds_write2_b32 v242, v170, v171 offset1:1
	ds_write2_b32 v242, v172, v173 offset0:2 offset1:3
	v_add_u32_e32 v242, 0x410, v242
	s_waitcnt vmcnt(9)
	v_mul_f32_e32 v174, v216, v174
	v_mul_f32_e32 v175, v216, v175
	v_mul_f32_e32 v176, v216, v176
	v_mul_f32_e32 v177, v216, v177
	ds_write2_b32 v242, v174, v175 offset1:1
	ds_write2_b32 v242, v176, v177 offset0:2 offset1:3
	v_add_u32_e32 v242, 0x410, v242
	s_waitcnt vmcnt(8)
	v_mul_f32_e32 v178, v217, v178
	v_mul_f32_e32 v179, v217, v179
	v_mul_f32_e32 v180, v217, v180
	v_mul_f32_e32 v181, v217, v181
	ds_write2_b32 v242, v178, v179 offset1:1
	ds_write2_b32 v242, v180, v181 offset0:2 offset1:3
	v_add_u32_e32 v242, 0x410, v242
	s_waitcnt vmcnt(7)
	v_mul_f32_e32 v182, v218, v182
	v_mul_f32_e32 v183, v218, v183
	v_mul_f32_e32 v184, v218, v184
	v_mul_f32_e32 v185, v218, v185
	ds_write2_b32 v242, v182, v183 offset1:1
	ds_write2_b32 v242, v184, v185 offset0:2 offset1:3
	v_add_u32_e32 v242, 0x410, v242
	s_waitcnt vmcnt(6)
	v_mul_f32_e32 v186, v219, v186
	v_mul_f32_e32 v187, v219, v187
	v_mul_f32_e32 v188, v219, v188
	v_mul_f32_e32 v189, v219, v189
	ds_write2_b32 v242, v186, v187 offset1:1
	ds_write2_b32 v242, v188, v189 offset0:2 offset1:3
	v_add_u32_e32 v242, 0x410, v242
	s_waitcnt vmcnt(5)
	v_mul_f32_e32 v190, v220, v190
	v_mul_f32_e32 v191, v220, v191
	v_mul_f32_e32 v192, v220, v192
	v_mul_f32_e32 v193, v220, v193
	ds_write2_b32 v242, v190, v191 offset1:1
	ds_write2_b32 v242, v192, v193 offset0:2 offset1:3
	v_add_u32_e32 v242, 0x410, v242
	s_waitcnt vmcnt(4)
	v_mul_f32_e32 v108, v221, v108
	v_mul_f32_e32 v109, v221, v109
	v_mul_f32_e32 v110, v221, v110
	v_mul_f32_e32 v111, v221, v111
	ds_write2_b32 v242, v108, v109 offset1:1
	ds_write2_b32 v242, v110, v111 offset0:2 offset1:3
	v_add_u32_e32 v242, 0x410, v242
	s_waitcnt vmcnt(3)
; #define LAS __attribute__((address_space(3)))
; __device__ __forceinline__ unsigned pk2(float lo, float hi) { return f2bf(lo) | (f2bf(hi) << 16); }
; #define LDS_WAIT() asm volatile("s_waitcnt lgkmcnt(0)" ::: "memory")
; __device__ __forceinline__ void tr_item(const float* W, int ldn, int col0, int k0, const float* g, bf16* WT, int ldk, int drow0, LAS float* scr, int lane) {
;     ...
;     LDS_WAIT(); asm volatile("" ::: "memory");
;     const int c = lane & 7;
; #pragma unroll
;     for (int j = 0; j < 8; ++j) { const int n = (lane >> 3) + 8 * j; const LAS float* s = scr + (8 * c) * 65 + n;
;         v4u o; o.x = pk2(s[0 * 65], s[1 * 65]); o.y = pk2(s[2 * 65], s[3 * 65]); o.z = pk2(s[4 * 65], s[5 * 65]); o.w = pk2(s[6 * 65], s[7 * 65]);
;         *(v4u*)(WT + (size_t)(drow0 + n) * ldk + k0 + 8 * c) = o; }
	v_mul_f32_e32 v112, v222, v112
	v_mul_f32_e32 v113, v222, v113
	v_mul_f32_e32 v114, v222, v114
	v_mul_f32_e32 v115, v222, v115
	ds_write2_b32 v242, v112, v113 offset1:1
	ds_write2_b32 v242, v114, v115 offset0:2 offset1:3
	v_add_u32_e32 v242, 0x410, v242
	s_waitcnt vmcnt(2)
	v_mul_f32_e32 v116, v223, v116
	v_mul_f32_e32 v117, v223, v117
	v_mul_f32_e32 v118, v223, v118
	v_mul_f32_e32 v119, v223, v119
	ds_write2_b32 v242, v116, v117 offset1:1
	ds_write2_b32 v242, v118, v119 offset0:2 offset1:3
	v_add_u32_e32 v242, 0x410, v242
	s_waitcnt vmcnt(1)
	v_mul_f32_e32 v120, v230, v120
	v_mul_f32_e32 v121, v230, v121
	v_mul_f32_e32 v122, v230, v122
	v_mul_f32_e32 v123, v230, v123
	ds_write2_b32 v242, v120, v121 offset1:1
	ds_write2_b32 v242, v122, v123 offset0:2 offset1:3
	v_add_u32_e32 v242, 0x410, v242
	s_waitcnt vmcnt(0)
	v_mul_f32_e32 v124, v231, v124
	v_mul_f32_e32 v125, v231, v125
	v_mul_f32_e32 v126, v231, v126
	v_mul_f32_e32 v127, v231, v127
	ds_write2_b32 v242, v124, v125 offset1:1
	ds_write2_b32 v242, v126, v127 offset0:2 offset1:3
	s_waitcnt lgkmcnt(0)
	ds_read2_b32 v[146:147], v48 offset0:0 offset1:65
	ds_read2_b32 v[148:149], v48 offset0:130 offset1:195
	ds_read2_b32 v[150:151], v243 offset0:4 offset1:69
	ds_read2_b32 v[152:153], v243 offset0:134 offset1:199
	ds_read2_b32 v[154:155], v48 offset0:8 offset1:73
	ds_read2_b32 v[156:157], v48 offset0:138 offset1:203
	ds_read2_b32 v[158:159], v243 offset0:12 offset1:77
	ds_read2_b32 v[160:161], v243 offset0:142 offset1:207
	ds_read2_b32 v[166:167], v48 offset0:16 offset1:81
	ds_read2_b32 v[168:169], v48 offset0:146 offset1:211
	ds_read2_b32 v[170:171], v243 offset0:20 offset1:85
	ds_read2_b32 v[172:173], v243 offset0:150 offset1:215
	s_waitcnt lgkmcnt(8)
	v_cvt_pk_bf16_f32 v146, v146, v147
	v_cvt_pk_bf16_f32 v147, v148, v149
	v_cvt_pk_bf16_f32 v148, v150, v151
	v_cvt_pk_bf16_f32 v149, v152, v153
	global_store_dwordx4 v244, v[146:149], s[24:25]
	ds_read2_b32 v[174:175], v48 offset0:24 offset1:89
	ds_read2_b32 v[176:177], v48 offset0:154 offset1:219
	ds_read2_b32 v[178:179], v243 offset0:28 offset1:93
	ds_read2_b32 v[180:181], v243 offset0:158 offset1:223
	s_waitcnt lgkmcnt(8)
	v_cvt_pk_bf16_f32 v154, v154, v155
	v_cvt_pk_bf16_f32 v155, v156, v157
	v_cvt_pk_bf16_f32 v156, v158, v159
	v_cvt_pk_bf16_f32 v157, v160, v161
	global_store_dwordx4 v245, v[154:157], s[24:25]
	ds_read2_b32 v[182:183], v48 offset0:32 offset1:97
	ds_read2_b32 v[184:185], v48 offset0:162 offset1:227
	ds_read2_b32 v[186:187], v243 offset0:36 offset1:101
	ds_read2_b32 v[188:189], v243 offset0:166 offset1:231
	s_waitcnt lgkmcnt(8)
	v_cvt_pk_bf16_f32 v166, v166, v167
	v_cvt_pk_bf16_f32 v167, v168, v169
	v_cvt_pk_bf16_f32 v168, v170, v171
	v_cvt_pk_bf16_f32 v169, v172, v173
	global_store_dwordx4 v246, v[166:169], s[24:25]
	ds_read2_b32 v[108:109], v48 offset0:40 offset1:105
	ds_read2_b32 v[110:111], v48 offset0:170 offset1:235
	ds_read2_b32 v[112:113], v243 offset0:44 offset1:109
	ds_read2_b32 v[114:115], v243 offset0:174 offset1:239
	s_waitcnt lgkmcnt(8)
	v_cvt_pk_bf16_f32 v174, v174, v175
	v_cvt_pk_bf16_f32 v175, v176, v177
	v_cvt_pk_bf16_f32 v176, v178, v179
	v_cvt_pk_bf16_f32 v177, v180, v181
	global_store_dwordx4 v247, v[174:177], s[24:25]
	ds_read2_b32 v[116:117], v48 offset0:48 offset1:113
	ds_read2_b32 v[118:119], v48 offset0:178 offset1:243
	ds_read2_b32 v[120:121], v243 offset0:52 offset1:117
	ds_read2_b32 v[122:123], v243 offset0:182 offset1:247
	s_waitcnt lgkmcnt(8)
	v_cvt_pk_bf16_f32 v182, v182, v183
	v_cvt_pk_bf16_f32 v183, v184, v185
	v_cvt_pk_bf16_f32 v184, v186, v187
	v_cvt_pk_bf16_f32 v185, v188, v189
	global_store_dwordx4 v248, v[182:185], s[24:25]
	ds_read2_b32 v[124:125], v48 offset0:56 offset1:121
	ds_read2_b32 v[126:127], v48 offset0:186 offset1:251
	ds_read2_b32 v[128:129], v243 offset0:60 offset1:125
	ds_read2_b32 v[130:131], v243 offset0:190 offset1:255
	s_waitcnt lgkmcnt(8)
	v_cvt_pk_bf16_f32 v108, v108, v109
	v_cvt_pk_bf16_f32 v109, v110, v111
	v_cvt_pk_bf16_f32 v110, v112, v113
	v_cvt_pk_bf16_f32 v111, v114, v115
	global_store_dwordx4 v249, v[108:111], s[24:25]
	s_waitcnt lgkmcnt(4)
	v_cvt_pk_bf16_f32 v116, v116, v117
	v_cvt_pk_bf16_f32 v117, v118, v119
	v_cvt_pk_bf16_f32 v118, v120, v121
	v_cvt_pk_bf16_f32 v119, v122, v123
	global_store_dwordx4 v250, v[116:119], s[24:25]
	s_waitcnt lgkmcnt(0)
	v_cvt_pk_bf16_f32 v124, v124, v125
	v_cvt_pk_bf16_f32 v125, v126, v127
	v_cvt_pk_bf16_f32 v126, v128, v129
	v_cvt_pk_bf16_f32 v127, v130, v131
	global_store_dwordx4 v251, v[124:127], s[24:25]
	s_addk_i32 s10, 0x400
	s_cmpk_lt_u32 s10, 0xc00
	s_cbranch_scc1 .Lofl_item
